# on top of previous: first seam uses the XCD barrier instead of the cooperative-groups grid sync; unit-start vmcnt(0) dropped in the RES GEMM too
# baseline (speedup 1.0000x reference)
.LBB0_308:
	s_add_u32 s43, s8, s28
	s_addc_u32 s52, s9, s21
	s_add_u32 s53, s10, 0x100
	s_addc_u32 s63, s11, 0
	s_mov_b64 s[10:11], 0
	s_waitcnt lgkmcnt(0)
	s_add_u32 vcc_lo, s10, 1
	s_addc_u32 vcc_hi, s11, 0
	s_add_u32 s46, s10, 2
	s_addc_u32 s47, s11, 0
	s_lshl_b64 s[48:49], s[46:47], s54
	s_add_u32 s11, s8, s48
	s_addc_u32 s48, s9, s49
	s_cmp_eq_u32 s94, s10
	s_cselect_b32 s50, s0, s11
	s_cselect_b32 s51, s1, s48
	s_cselect_b32 s48, s44, s53
	s_cselect_b32 s49, s45, s63
	s_add_u32 s10, s50, s14
	s_addc_u32 s11, s51, s15
	s_add_i32 s57, 0, 0x10000
	s_add_i32 s60, 0, 0x14000
	v_add_u32_e32 v70, s57, v197
	v_add_u32_e32 v94, s60, v197
	ds_read_b128 v[50:53], v70
	ds_read_b128 v[58:61], v70 offset:1024
	ds_read_b128 v[66:69], v70 offset:2048
	ds_read_b128 v[70:73], v70 offset:3072
	ds_read_b128 v[82:85], v94
	ds_read_b128 v[86:89], v94 offset:1024
	ds_read_b128 v[90:93], v94 offset:2048
	ds_read_b128 v[94:97], v94 offset:3072
	s_lshl_b64 vcc, vcc, s54
	s_add_u32 vcc_lo, s43, vcc_lo
	s_addc_u32 vcc_hi, s52, vcc_hi
	v_lshl_add_u64 v[214:215], vcc, 0, v[202:203]
	s_add_i32 m0, s61, 0xc000
	ds_read_b128 v[154:157], v221
	ds_read_b128 v[158:161], v221 offset:1024
	ds_read_b128 v[170:173], v221 offset:2048
	ds_read_b128 v[174:177], v221 offset:3072
	ds_read_b128 v[178:181], v221 offset:4096
	ds_read_b128 v[182:185], v221 offset:5120
	ds_read_b128 v[186:189], v221 offset:6144
	ds_read_b128 v[210:213], v221 offset:7168
	global_load_lds_dwordx4 v[214:215], off
	v_lshl_add_u64 v[214:215], vcc, 0, v[204:205]
	s_add_i32 m0, s61, 0xe000
	s_nop 0
	global_load_lds_dwordx4 v[214:215], off
	s_waitcnt vmcnt(8)
	s_waitcnt lgkmcnt(0)
	s_setprio 1
	s_barrier
	v_mfma_f32_16x16x32_bf16 v[166:169], v[50:53], v[154:157], 0
	v_mfma_f32_16x16x32_bf16 v[162:165], v[66:69], v[154:157], 0
	v_mfma_f32_16x16x32_bf16 v[150:153], v[50:53], v[170:173], 0
	v_mfma_f32_16x16x32_bf16 v[146:149], v[66:69], v[170:173], 0
	v_mfma_f32_16x16x32_bf16 v[142:145], v[50:53], v[178:181], 0
	v_mfma_f32_16x16x32_bf16 v[138:141], v[66:69], v[178:181], 0
	v_mfma_f32_16x16x32_bf16 v[134:137], v[50:53], v[186:189], 0
	v_mfma_f32_16x16x32_bf16 v[130:133], v[66:69], v[186:189], 0
	v_mfma_f32_16x16x32_bf16 v[166:169], v[58:61], v[158:161], v[166:169]
	v_mfma_f32_16x16x32_bf16 v[162:165], v[70:73], v[158:161], v[162:165]
	v_mfma_f32_16x16x32_bf16 v[150:153], v[58:61], v[174:177], v[150:153]
	v_mfma_f32_16x16x32_bf16 v[146:149], v[70:73], v[174:177], v[146:149]
	v_mfma_f32_16x16x32_bf16 v[142:145], v[58:61], v[182:185], v[142:145]
	v_mfma_f32_16x16x32_bf16 v[138:141], v[70:73], v[182:185], v[138:141]
	v_mfma_f32_16x16x32_bf16 v[134:137], v[58:61], v[210:213], v[134:137]
	v_mfma_f32_16x16x32_bf16 v[130:133], v[70:73], v[210:213], v[130:133]
	v_mfma_f32_16x16x32_bf16 v[126:129], v[82:85], v[154:157], 0
	v_mfma_f32_16x16x32_bf16 v[122:125], v[90:93], v[154:157], 0
	v_mfma_f32_16x16x32_bf16 v[118:121], v[82:85], v[170:173], 0
	v_mfma_f32_16x16x32_bf16 v[114:117], v[90:93], v[170:173], 0
	v_mfma_f32_16x16x32_bf16 v[110:113], v[82:85], v[178:181], 0
	v_mfma_f32_16x16x32_bf16 v[106:109], v[90:93], v[178:181], 0
	v_mfma_f32_16x16x32_bf16 v[102:105], v[82:85], v[186:189], 0
	v_mfma_f32_16x16x32_bf16 v[98:101], v[90:93], v[186:189], 0
	v_mfma_f32_16x16x32_bf16 v[126:129], v[86:89], v[158:161], v[126:129]
	v_mfma_f32_16x16x32_bf16 v[122:125], v[94:97], v[158:161], v[122:125]
	v_mfma_f32_16x16x32_bf16 v[118:121], v[86:89], v[174:177], v[118:121]
	v_mfma_f32_16x16x32_bf16 v[114:117], v[94:97], v[174:177], v[114:117]
	v_mfma_f32_16x16x32_bf16 v[110:113], v[86:89], v[182:185], v[110:113]
	v_mfma_f32_16x16x32_bf16 v[106:109], v[94:97], v[182:185], v[106:109]
	v_mfma_f32_16x16x32_bf16 v[102:105], v[86:89], v[210:213], v[102:105]
	v_mfma_f32_16x16x32_bf16 v[98:101], v[94:97], v[210:213], v[98:101]
	s_barrier
	s_setprio 0
	s_add_i32 s57, s57, s29
	v_lshl_add_u64 v[214:215], s[48:49], 0, v[190:191]
	s_mov_b32 m0, s57
	ds_read_b128 v[154:157], v221 offset:16384
	ds_read_b128 v[158:161], v221 offset:17408
	ds_read_b128 v[170:173], v221 offset:18432
	ds_read_b128 v[174:177], v221 offset:19456
	ds_read_b128 v[178:181], v221 offset:20480
	ds_read_b128 v[182:185], v221 offset:21504
	ds_read_b128 v[186:189], v221 offset:22528
	ds_read_b128 v[210:213], v221 offset:23552
	global_load_lds_dwordx4 v[214:215], off
	s_add_i32 m0, s57, 0x2000
	v_lshl_add_u64 v[216:217], s[48:49], 0, v[206:207]
	s_add_u32 s48, s48, s2
	s_addc_u32 s49, s49, 0
	s_add_i32 s57, s60, s29
	global_load_lds_dwordx4 v[216:217], off
	v_lshl_add_u64 v[218:219], s[48:49], 0, v[190:191]
	s_mov_b32 m0, s57
	v_lshl_add_u64 v[222:223], s[48:49], 0, v[206:207]
	global_load_lds_dwordx4 v[218:219], off
	s_add_i32 m0, s57, 0x2000
	v_lshl_add_u64 v[234:235], s[50:51], 0, v[202:203]
	global_load_lds_dwordx4 v[222:223], off
	s_mov_b32 m0, s61
	s_nop 0
	global_load_lds_dwordx4 v[234:235], off
	v_lshl_add_u64 v[234:235], s[50:51], 0, v[204:205]
	s_mov_b32 m0, s66
	s_nop 0
	global_load_lds_dwordx4 v[234:235], off
	s_waitcnt vmcnt(8)
	s_waitcnt lgkmcnt(0)
	s_setprio 1
	s_barrier
	v_mfma_f32_16x16x32_bf16 v[78:81], v[50:53], v[154:157], 0
	v_mfma_f32_16x16x32_bf16 v[74:77], v[66:69], v[154:157], 0
	v_mfma_f32_16x16x32_bf16 v[62:65], v[50:53], v[170:173], 0
	v_mfma_f32_16x16x32_bf16 v[54:57], v[66:69], v[170:173], 0
	v_mfma_f32_16x16x32_bf16 v[46:49], v[50:53], v[178:181], 0
	v_mfma_f32_16x16x32_bf16 v[42:45], v[66:69], v[178:181], 0
	v_mfma_f32_16x16x32_bf16 v[38:41], v[50:53], v[186:189], 0
	v_mfma_f32_16x16x32_bf16 v[34:37], v[66:69], v[186:189], 0
	v_mfma_f32_16x16x32_bf16 v[78:81], v[58:61], v[158:161], v[78:81]
	v_mfma_f32_16x16x32_bf16 v[74:77], v[70:73], v[158:161], v[74:77]
	v_mfma_f32_16x16x32_bf16 v[62:65], v[58:61], v[174:177], v[62:65]
	v_mfma_f32_16x16x32_bf16 v[54:57], v[70:73], v[174:177], v[54:57]
	v_mfma_f32_16x16x32_bf16 v[46:49], v[58:61], v[182:185], v[46:49]
	v_mfma_f32_16x16x32_bf16 v[42:45], v[70:73], v[182:185], v[42:45]
	v_mfma_f32_16x16x32_bf16 v[38:41], v[58:61], v[210:213], v[38:41]
	v_mfma_f32_16x16x32_bf16 v[34:37], v[70:73], v[210:213], v[34:37]
	v_mfma_f32_16x16x32_bf16 v[30:33], v[82:85], v[154:157], 0
	v_mfma_f32_16x16x32_bf16 v[26:29], v[90:93], v[154:157], 0
	v_mfma_f32_16x16x32_bf16 v[22:25], v[82:85], v[170:173], 0
	v_mfma_f32_16x16x32_bf16 v[18:21], v[90:93], v[170:173], 0
	v_mfma_f32_16x16x32_bf16 v[14:17], v[82:85], v[178:181], 0
	v_mfma_f32_16x16x32_bf16 v[10:13], v[90:93], v[178:181], 0
	v_mfma_f32_16x16x32_bf16 v[6:9], v[82:85], v[186:189], 0
	v_mfma_f32_16x16x32_bf16 v[2:5], v[90:93], v[186:189], 0
	v_mfma_f32_16x16x32_bf16 v[30:33], v[86:89], v[158:161], v[30:33]
	v_mfma_f32_16x16x32_bf16 v[26:29], v[94:97], v[158:161], v[26:29]
	v_mfma_f32_16x16x32_bf16 v[22:25], v[86:89], v[174:177], v[22:25]
	v_mfma_f32_16x16x32_bf16 v[18:21], v[94:97], v[174:177], v[18:21]
	v_mfma_f32_16x16x32_bf16 v[14:17], v[86:89], v[182:185], v[14:17]
	v_mfma_f32_16x16x32_bf16 v[10:13], v[94:97], v[182:185], v[10:13]
	v_mfma_f32_16x16x32_bf16 v[6:9], v[86:89], v[210:213], v[6:9]
	v_mfma_f32_16x16x32_bf16 v[2:5], v[94:97], v[210:213], v[2:5]
	s_barrier
	s_setprio 0
	s_add_i32 s57, 0, 0x18000
	s_add_i32 s60, 0, 0x1c000
	v_add_u32_e32 v70, s57, v197
	v_add_u32_e32 v94, s60, v197
	ds_read_b128 v[50:53], v70
	ds_read_b128 v[58:61], v70 offset:1024
	ds_read_b128 v[66:69], v70 offset:2048
	ds_read_b128 v[70:73], v70 offset:3072
	ds_read_b128 v[82:85], v94
	ds_read_b128 v[86:89], v94 offset:1024
	ds_read_b128 v[90:93], v94 offset:2048
	ds_read_b128 v[94:97], v94 offset:3072
	s_add_u32 s48, s50, s28
	s_addc_u32 s49, s51, s21
	s_mov_b32 m0, s67
	v_lshl_add_u64 v[234:235], s[48:49], 0, v[202:203]
	ds_read_b128 v[154:157], v221 offset:32768
	ds_read_b128 v[158:161], v221 offset:33792
	ds_read_b128 v[170:173], v221 offset:34816
	ds_read_b128 v[174:177], v221 offset:35840
	ds_read_b128 v[178:181], v221 offset:36864
	ds_read_b128 v[182:185], v221 offset:37888
	ds_read_b128 v[186:189], v221 offset:38912
	ds_read_b128 v[210:213], v221 offset:39936
	global_load_lds_dwordx4 v[234:235], off
	v_lshl_add_u64 v[234:235], s[48:49], 0, v[204:205]
	s_mov_b32 m0, s69
	s_nop 0
	global_load_lds_dwordx4 v[234:235], off
	s_waitcnt vmcnt(8)
	s_waitcnt lgkmcnt(0)
	s_setprio 1
	s_barrier
	v_mfma_f32_16x16x32_bf16 v[166:169], v[50:53], v[154:157], v[166:169]
	v_mfma_f32_16x16x32_bf16 v[162:165], v[66:69], v[154:157], v[162:165]
	v_mfma_f32_16x16x32_bf16 v[150:153], v[50:53], v[170:173], v[150:153]
	v_mfma_f32_16x16x32_bf16 v[146:149], v[66:69], v[170:173], v[146:149]
	v_mfma_f32_16x16x32_bf16 v[142:145], v[50:53], v[178:181], v[142:145]
	v_mfma_f32_16x16x32_bf16 v[138:141], v[66:69], v[178:181], v[138:141]
	v_mfma_f32_16x16x32_bf16 v[134:137], v[50:53], v[186:189], v[134:137]
	v_mfma_f32_16x16x32_bf16 v[130:133], v[66:69], v[186:189], v[130:133]
	v_mfma_f32_16x16x32_bf16 v[166:169], v[58:61], v[158:161], v[166:169]
	v_mfma_f32_16x16x32_bf16 v[162:165], v[70:73], v[158:161], v[162:165]
	v_mfma_f32_16x16x32_bf16 v[150:153], v[58:61], v[174:177], v[150:153]
	v_mfma_f32_16x16x32_bf16 v[146:149], v[70:73], v[174:177], v[146:149]
	v_mfma_f32_16x16x32_bf16 v[142:145], v[58:61], v[182:185], v[142:145]
	v_mfma_f32_16x16x32_bf16 v[138:141], v[70:73], v[182:185], v[138:141]
	v_mfma_f32_16x16x32_bf16 v[134:137], v[58:61], v[210:213], v[134:137]
	v_mfma_f32_16x16x32_bf16 v[130:133], v[70:73], v[210:213], v[130:133]
	v_mfma_f32_16x16x32_bf16 v[126:129], v[82:85], v[154:157], v[126:129]
	v_mfma_f32_16x16x32_bf16 v[122:125], v[90:93], v[154:157], v[122:125]
	v_mfma_f32_16x16x32_bf16 v[118:121], v[82:85], v[170:173], v[118:121]
	v_mfma_f32_16x16x32_bf16 v[114:117], v[90:93], v[170:173], v[114:117]
	v_mfma_f32_16x16x32_bf16 v[110:113], v[82:85], v[178:181], v[110:113]
	v_mfma_f32_16x16x32_bf16 v[106:109], v[90:93], v[178:181], v[106:109]
	v_mfma_f32_16x16x32_bf16 v[102:105], v[82:85], v[186:189], v[102:105]
	v_mfma_f32_16x16x32_bf16 v[98:101], v[90:93], v[186:189], v[98:101]
	v_mfma_f32_16x16x32_bf16 v[126:129], v[86:89], v[158:161], v[126:129]
	v_mfma_f32_16x16x32_bf16 v[122:125], v[94:97], v[158:161], v[122:125]
	v_mfma_f32_16x16x32_bf16 v[118:121], v[86:89], v[174:177], v[118:121]
	v_mfma_f32_16x16x32_bf16 v[114:117], v[94:97], v[174:177], v[114:117]
	v_mfma_f32_16x16x32_bf16 v[110:113], v[86:89], v[182:185], v[110:113]
	v_mfma_f32_16x16x32_bf16 v[106:109], v[94:97], v[182:185], v[106:109]
	v_mfma_f32_16x16x32_bf16 v[102:105], v[86:89], v[210:213], v[102:105]
	v_mfma_f32_16x16x32_bf16 v[98:101], v[94:97], v[210:213], v[98:101]
	s_barrier
	s_setprio 0
	s_add_i32 s48, s57, s29
	v_lshl_add_u64 v[214:215], v[214:215], 0, s[64:65]
	s_mov_b32 m0, s48
	ds_read_b128 v[154:157], v221 offset:49152
	ds_read_b128 v[158:161], v221 offset:50176
	ds_read_b128 v[170:173], v221 offset:51200
	ds_read_b128 v[174:177], v221 offset:52224
	ds_read_b128 v[178:181], v221 offset:53248
	ds_read_b128 v[182:185], v221 offset:54272
	ds_read_b128 v[186:189], v221 offset:55296
	ds_read_b128 v[210:213], v221 offset:56320
	global_load_lds_dwordx4 v[214:215], off
	v_lshl_add_u64 v[214:215], v[216:217], 0, s[64:65]
	s_add_i32 m0, s48, 0x2000
	s_add_i32 s48, s60, s29
	global_load_lds_dwordx4 v[214:215], off
	v_lshl_add_u64 v[214:215], v[218:219], 0, s[64:65]
	s_mov_b32 m0, s48
	s_nop 0
	global_load_lds_dwordx4 v[214:215], off
	v_lshl_add_u64 v[214:215], v[222:223], 0, s[64:65]
	s_add_i32 m0, s48, 0x2000
	s_nop 0
	global_load_lds_dwordx4 v[214:215], off
	v_lshl_add_u64 v[214:215], s[10:11], 0, v[202:203]
	s_mov_b32 m0, s89
	s_nop 0
	global_load_lds_dwordx4 v[214:215], off
	v_lshl_add_u64 v[214:215], s[10:11], 0, v[204:205]
	s_mov_b32 m0, s91
	s_nop 0
	global_load_lds_dwordx4 v[214:215], off
	s_waitcnt vmcnt(8)
	s_waitcnt lgkmcnt(0)
	s_setprio 1
	s_barrier
	v_mfma_f32_16x16x32_bf16 v[78:81], v[50:53], v[154:157], v[78:81]
	v_mfma_f32_16x16x32_bf16 v[74:77], v[66:69], v[154:157], v[74:77]
	v_mfma_f32_16x16x32_bf16 v[62:65], v[50:53], v[170:173], v[62:65]
	v_mfma_f32_16x16x32_bf16 v[54:57], v[66:69], v[170:173], v[54:57]
	v_mfma_f32_16x16x32_bf16 v[46:49], v[50:53], v[178:181], v[46:49]
	v_mfma_f32_16x16x32_bf16 v[42:45], v[66:69], v[178:181], v[42:45]
	v_mfma_f32_16x16x32_bf16 v[38:41], v[50:53], v[186:189], v[38:41]
	v_mfma_f32_16x16x32_bf16 v[34:37], v[66:69], v[186:189], v[34:37]
	v_mfma_f32_16x16x32_bf16 v[78:81], v[58:61], v[158:161], v[78:81]
	v_mfma_f32_16x16x32_bf16 v[74:77], v[70:73], v[158:161], v[74:77]
	v_mfma_f32_16x16x32_bf16 v[62:65], v[58:61], v[174:177], v[62:65]
	v_mfma_f32_16x16x32_bf16 v[54:57], v[70:73], v[174:177], v[54:57]
	v_mfma_f32_16x16x32_bf16 v[46:49], v[58:61], v[182:185], v[46:49]
	v_mfma_f32_16x16x32_bf16 v[42:45], v[70:73], v[182:185], v[42:45]
	v_mfma_f32_16x16x32_bf16 v[38:41], v[58:61], v[210:213], v[38:41]
	v_mfma_f32_16x16x32_bf16 v[34:37], v[70:73], v[210:213], v[34:37]
	v_mfma_f32_16x16x32_bf16 v[30:33], v[82:85], v[154:157], v[30:33]
	v_mfma_f32_16x16x32_bf16 v[26:29], v[90:93], v[154:157], v[26:29]
	v_mfma_f32_16x16x32_bf16 v[22:25], v[82:85], v[170:173], v[22:25]
	v_mfma_f32_16x16x32_bf16 v[18:21], v[90:93], v[170:173], v[18:21]
	v_mfma_f32_16x16x32_bf16 v[14:17], v[82:85], v[178:181], v[14:17]
	v_mfma_f32_16x16x32_bf16 v[10:13], v[90:93], v[178:181], v[10:13]
	v_mfma_f32_16x16x32_bf16 v[6:9], v[82:85], v[186:189], v[6:9]
	v_mfma_f32_16x16x32_bf16 v[2:5], v[90:93], v[186:189], v[2:5]
	v_mfma_f32_16x16x32_bf16 v[30:33], v[86:89], v[158:161], v[30:33]
	v_mfma_f32_16x16x32_bf16 v[26:29], v[94:97], v[158:161], v[26:29]
	v_mfma_f32_16x16x32_bf16 v[22:25], v[86:89], v[174:177], v[22:25]
	v_mfma_f32_16x16x32_bf16 v[18:21], v[94:97], v[174:177], v[18:21]
	v_mfma_f32_16x16x32_bf16 v[14:17], v[86:89], v[182:185], v[14:17]
	v_mfma_f32_16x16x32_bf16 v[10:13], v[94:97], v[182:185], v[10:13]
	v_mfma_f32_16x16x32_bf16 v[6:9], v[86:89], v[210:213], v[6:9]
	v_mfma_f32_16x16x32_bf16 v[2:5], v[94:97], v[210:213], v[2:5]
	s_barrier
	s_setprio 0
	s_add_u32 s53, s53, 0x100
	s_addc_u32 s63, s63, 0
	s_cmp_ge_u32 s46, s71
	s_mov_b64 s[10:11], s[46:47]
	s_cbranch_scc1 .Lpeel_exit_s

.LBB0_800:
	v_readlane_b32 s0, v255, 8
	v_readlane_b32 s1, v255, 9
	s_cmp_lg_u32 s3, s0
	s_mov_b64 s[0:1], -1
	s_getreg_b32 s3, hwreg(HW_REG_XCC_ID, 0, 4)
	s_waitcnt vmcnt(0)
	s_waitcnt lgkmcnt(0)
	s_barrier
	s_mov_b64 s[0:1], exec
	v_readlane_b32 s4, v255, 2
	v_readlane_b32 s5, v255, 3
	s_and_b64 s[4:5], s[0:1], s[4:5]
	s_mov_b64 exec, s[4:5]
	s_cbranch_execz .LBB0_853
	v_readlane_b32 s4, v255, 30
	s_waitcnt vmcnt(0) expcnt(0) lgkmcnt(0)
	s_and_b32 s3, s3, 15
	v_mov_b32_e32 v1, s4
	ds_read_b32 v3, v1
	v_readlane_b32 s4, v255, 31
	s_waitcnt lgkmcnt(0)
	v_cmp_ne_u32_e32 vcc, 0, v3
	v_mov_b32_e32 v1, s4
	ds_read_b32 v2, v1
	s_cbranch_vccnz .LBB0_817
	s_add_u32 s4, s34, 0x22c00200
	s_addc_u32 s5, s35, 0
	s_add_u32 s6, s34, 0x22c00400
	s_addc_u32 s7, s35, 0
	s_add_u32 s8, s34, 0x22c00500
	s_addc_u32 s9, s35, 0
	s_add_u32 s10, s34, 0x22c00600
	s_addc_u32 s11, s35, 0
	s_add_u32 s12, s34, 0x22c00700
	s_addc_u32 s13, s35, 0
	s_add_u32 s14, s34, 0x22c00800
	s_addc_u32 s15, s35, 0
	s_add_u32 s16, s34, 0x22c00900
	s_addc_u32 s17, s35, 0
	s_add_u32 s18, s34, 0x22c00a00
	s_addc_u32 s19, s35, 0
	s_add_u32 s26, s34, 0x22c00b00
	s_addc_u32 s27, s35, 0
	s_add_u32 s42, s34, 0x22c00c00
	s_addc_u32 s43, s35, 0
	s_add_u32 s44, s34, 0x22c00d00
	s_addc_u32 s45, s35, 0
	s_add_u32 s46, s34, 0x22c00e00
	s_addc_u32 s47, s35, 0
	s_add_u32 s50, s34, 0x22c00f00
	s_addc_u32 s51, s35, 0
	s_add_u32 s48, s34, 0x22c01000
	s_addc_u32 s49, s35, 0
	s_add_u32 s52, s34, 0x22c01100
	s_addc_u32 s53, s35, 0
	s_add_u32 s58, s34, 0x22c01200
	s_addc_u32 s59, s35, 0
	s_add_u32 s62, s34, 0x22c01300
	s_addc_u32 s63, s35, 0
	s_mov_b32 s21, 1
	s_branch .LBB0_805
